# EpiProj: drop redundant vmcnt(0) store-drains in gate/rope blocks
# baseline (speedup 1.0000x reference)
.LBB0_149:
	s_waitcnt lgkmcnt(0)
	v_mov_b64_e32 v[160:161], s[52:53]
	v_mad_i64_i32 v[160:161], s[0:1], v206, s15, v[160:161]
	v_cvt_pk_bf16_f32 v162, v234, v235
	v_cvt_pk_bf16_f32 v163, v166, v167
	v_lshl_add_u64 v[160:161], v[204:205], 1, v[160:161]
	v_mov_b32_e32 v231, v230
	v_cvt_pk_bf16_f32 v164, v236, v237
	v_cvt_pk_bf16_f32 v165, v232, v233
	global_store_dwordx4 v[160:161], v[162:165], off
	s_and_b64 vcc, exec, s[42:43]
	v_pk_mul_f32 v[166:167], v[144:145], v[230:231]
	v_mov_b32_e32 v162, v230
	v_mov_b32_e32 v163, v230
	v_pk_mul_f32 v[150:151], v[150:151], v[162:163]
	v_pk_mul_f32 v[164:165], v[148:149], v[230:231]
	v_pk_mul_f32 v[162:163], v[146:147], v[162:163]
	s_cbranch_vccnz .LBB0_157
	ds_swizzle_b32 v146, v164 offset:swizzle(SWAP,16)
	ds_swizzle_b32 v144, v166 offset:swizzle(SWAP,16)
	ds_swizzle_b32 v147, v165 offset:swizzle(SWAP,16)
	ds_swizzle_b32 v145, v167 offset:swizzle(SWAP,16)
	ds_swizzle_b32 v232, v150 offset:swizzle(SWAP,16)
	ds_swizzle_b32 v230, v162 offset:swizzle(SWAP,16)
	ds_swizzle_b32 v233, v151 offset:swizzle(SWAP,16)
	ds_swizzle_b32 v231, v163 offset:swizzle(SWAP,16)
	s_and_saveexec_b64 s[0:1], s[46:47]
	s_xor_b64 s[0:1], exec, s[0:1]
	s_cbranch_execz .LBB0_154
	s_and_saveexec_b64 s[4:5], s[44:45]
	s_cbranch_execz .LBB0_153
	s_waitcnt lgkmcnt(0)
	v_pk_mul_f32 v[146:147], v[172:173], v[146:147]
	v_pk_mul_f32 v[148:149], v[174:175], v[232:233]
	v_pk_fma_f32 v[164:165], v[164:165], v[168:169], v[146:147]
	v_pk_mul_f32 v[146:147], v[158:159], v[230:231]
	v_pk_mul_f32 v[144:145], v[156:157], v[144:145]
	v_pk_fma_f32 v[150:151], v[150:151], v[170:171], v[148:149]
	v_pk_fma_f32 v[162:163], v[162:163], v[154:155], v[146:147]
	v_pk_fma_f32 v[166:167], v[166:167], v[152:153], v[144:145]

.LBB0_154:
	s_andn2_saveexec_b64 s[0:1], s[0:1]
	s_cbranch_execz .LBB0_156
	s_waitcnt lgkmcnt(0)
	v_pk_mul_f32 v[146:147], v[172:173], v[146:147]
	v_pk_mul_f32 v[148:149], v[174:175], v[232:233]
	v_pk_fma_f32 v[164:165], v[164:165], v[168:169], v[146:147] neg_lo:[0,0,1] neg_hi:[0,0,1]
	v_pk_mul_f32 v[146:147], v[158:159], v[230:231]
	v_pk_mul_f32 v[144:145], v[156:157], v[144:145]
	v_pk_fma_f32 v[150:151], v[150:151], v[170:171], v[148:149] neg_lo:[0,0,1] neg_hi:[0,0,1]
	v_pk_fma_f32 v[162:163], v[162:163], v[154:155], v[146:147] neg_lo:[0,0,1] neg_hi:[0,0,1]
	v_pk_fma_f32 v[166:167], v[166:167], v[152:153], v[144:145] neg_lo:[0,0,1] neg_hi:[0,0,1]

.LBB0_157:
	s_and_b64 vcc, exec, s[40:41]
	s_cbranch_vccnz .LBB0_159
	s_waitcnt lgkmcnt(0)
	v_add_f32_e32 v144, v44, v164
	v_mul_f32_e32 v144, 0xbfb8aa3b, v144
	v_add_f32_e32 v145, v40, v166
	v_exp_f32_e32 v144, v144
	v_mul_f32_e32 v145, 0xbfb8aa3b, v145
	v_exp_f32_e32 v145, v145
	v_add_f32_e32 v146, v41, v167
	v_add_f32_e32 v144, 1.0, v144
	v_rcp_f32_e32 v164, v144
	v_add_f32_e32 v144, 1.0, v145
	v_add_f32_e32 v145, v45, v165
	v_mul_f32_e32 v145, 0xbfb8aa3b, v145
	v_exp_f32_e32 v145, v145
	v_mul_f32_e32 v146, 0xbfb8aa3b, v146
	v_exp_f32_e32 v146, v146
	v_rcp_f32_e32 v166, v144
	v_add_f32_e32 v144, 1.0, v145
	v_add_f32_e32 v145, v46, v150
	v_rcp_f32_e32 v165, v144
	v_add_f32_e32 v144, 1.0, v146
	v_mul_f32_e32 v145, 0xbfb8aa3b, v145
	v_add_f32_e32 v146, v42, v162
	v_exp_f32_e32 v145, v145
	v_mul_f32_e32 v146, 0xbfb8aa3b, v146
	v_exp_f32_e32 v146, v146
	v_rcp_f32_e32 v167, v144
	v_add_f32_e32 v144, 1.0, v145
	v_add_f32_e32 v145, v47, v151
	v_rcp_f32_e32 v150, v144
	v_add_f32_e32 v144, 1.0, v146
	v_mul_f32_e32 v145, 0xbfb8aa3b, v145
	v_add_f32_e32 v146, v43, v163
	v_exp_f32_e32 v145, v145
	v_mul_f32_e32 v146, 0xbfb8aa3b, v146
	v_exp_f32_e32 v146, v146
	v_rcp_f32_e32 v162, v144
	v_add_f32_e32 v144, 1.0, v145
	v_rcp_f32_e32 v151, v144
	v_add_f32_e32 v144, 1.0, v146
	v_rcp_f32_e32 v163, v144
.LBB0_159:
	s_waitcnt lgkmcnt(0)
	v_cvt_pk_bf16_f32 v144, v164, v165
	v_cvt_pk_bf16_f32 v145, v150, v151
	v_cvt_pk_bf16_f32 v146, v166, v167
	v_cvt_pk_bf16_f32 v147, v162, v163
	global_store_dwordx4 v[160:161], v[144:147], off offset:256
	v_pk_mul_f32 v[148:149], v[116:117], v[228:229] op_sel_hi:[1,0]
	s_and_b64 vcc, exec, s[42:43]
	v_pk_mul_f32 v[144:145], v[118:119], v[228:229] op_sel_hi:[1,0]
	v_pk_mul_f32 v[146:147], v[110:111], v[228:229] op_sel_hi:[1,0]
	v_pk_mul_f32 v[150:151], v[108:109], v[228:229] op_sel_hi:[1,0]
	s_cbranch_vccnz .LBB0_167
	ds_swizzle_b32 v116, v148 offset:swizzle(SWAP,16)
	ds_swizzle_b32 v108, v150 offset:swizzle(SWAP,16)
	ds_swizzle_b32 v117, v149 offset:swizzle(SWAP,16)
	ds_swizzle_b32 v109, v151 offset:swizzle(SWAP,16)
	ds_swizzle_b32 v162, v144 offset:swizzle(SWAP,16)
	ds_swizzle_b32 v160, v146 offset:swizzle(SWAP,16)
	ds_swizzle_b32 v163, v145 offset:swizzle(SWAP,16)
	ds_swizzle_b32 v161, v147 offset:swizzle(SWAP,16)
	s_and_saveexec_b64 s[0:1], s[46:47]
	s_xor_b64 s[0:1], exec, s[0:1]
	s_cbranch_execz .LBB0_164
	s_and_saveexec_b64 s[4:5], s[44:45]
	s_cbranch_execz .LBB0_163
	s_waitcnt lgkmcnt(0)
	v_pk_mul_f32 v[110:111], v[126:127], v[162:163]
	v_pk_mul_f32 v[116:117], v[124:125], v[116:117]
	v_pk_fma_f32 v[144:145], v[144:145], v[122:123], v[110:111]
	v_pk_mul_f32 v[110:111], v[114:115], v[160:161]
	v_pk_mul_f32 v[108:109], v[112:113], v[108:109]
	v_pk_fma_f32 v[148:149], v[148:149], v[120:121], v[116:117]
	v_pk_fma_f32 v[146:147], v[146:147], v[106:107], v[110:111]
	v_pk_fma_f32 v[150:151], v[150:151], v[104:105], v[108:109]

.LBB0_164:
	s_andn2_saveexec_b64 s[0:1], s[0:1]
	s_cbranch_execz .LBB0_166
	s_waitcnt lgkmcnt(0)
	v_pk_mul_f32 v[110:111], v[126:127], v[162:163]
	v_pk_mul_f32 v[116:117], v[124:125], v[116:117]
	v_pk_fma_f32 v[144:145], v[144:145], v[122:123], v[110:111] neg_lo:[0,0,1] neg_hi:[0,0,1]
	v_pk_mul_f32 v[110:111], v[114:115], v[160:161]
	v_pk_mul_f32 v[108:109], v[112:113], v[108:109]
	v_pk_fma_f32 v[148:149], v[148:149], v[120:121], v[116:117] neg_lo:[0,0,1] neg_hi:[0,0,1]
	v_pk_fma_f32 v[146:147], v[146:147], v[106:107], v[110:111] neg_lo:[0,0,1] neg_hi:[0,0,1]
	v_pk_fma_f32 v[150:151], v[150:151], v[104:105], v[108:109] neg_lo:[0,0,1] neg_hi:[0,0,1]

.LBB0_167:
	s_and_b64 vcc, exec, s[40:41]
	s_cbranch_vccnz .LBB0_169
	s_waitcnt lgkmcnt(0)
	v_add_f32_e32 v108, v60, v148
	v_mul_f32_e32 v108, 0xbfb8aa3b, v108
	v_add_f32_e32 v109, v56, v150
	v_exp_f32_e32 v108, v108
	v_mul_f32_e32 v109, 0xbfb8aa3b, v109
	v_exp_f32_e32 v109, v109
	v_add_f32_e32 v110, v57, v151
	v_add_f32_e32 v108, 1.0, v108
	v_rcp_f32_e32 v148, v108
	v_add_f32_e32 v108, 1.0, v109
	v_add_f32_e32 v109, v61, v149
	v_mul_f32_e32 v109, 0xbfb8aa3b, v109
	v_exp_f32_e32 v109, v109
	v_mul_f32_e32 v110, 0xbfb8aa3b, v110
	v_exp_f32_e32 v110, v110
	v_rcp_f32_e32 v150, v108
	v_add_f32_e32 v108, 1.0, v109
	v_add_f32_e32 v109, v62, v144
	v_rcp_f32_e32 v149, v108
	v_add_f32_e32 v108, 1.0, v110
	v_mul_f32_e32 v109, 0xbfb8aa3b, v109
	v_add_f32_e32 v110, v58, v146
	v_exp_f32_e32 v109, v109
	v_mul_f32_e32 v110, 0xbfb8aa3b, v110
	v_exp_f32_e32 v110, v110
	v_rcp_f32_e32 v151, v108
	v_add_f32_e32 v108, 1.0, v109
	v_add_f32_e32 v109, v63, v145
	v_rcp_f32_e32 v144, v108
	v_add_f32_e32 v108, 1.0, v110
	v_mul_f32_e32 v109, 0xbfb8aa3b, v109
	v_add_f32_e32 v110, v59, v147
	v_exp_f32_e32 v109, v109
	v_mul_f32_e32 v110, 0xbfb8aa3b, v110
	v_exp_f32_e32 v110, v110
	v_rcp_f32_e32 v146, v108
	v_add_f32_e32 v108, 1.0, v109
	v_rcp_f32_e32 v145, v108
	v_add_f32_e32 v108, 1.0, v110
	v_rcp_f32_e32 v147, v108
.LBB0_169:
	s_waitcnt lgkmcnt(0)
	v_mov_b64_e32 v[108:109], s[52:53]
	v_mad_i64_i32 v[108:109], s[0:1], v224, s15, v[108:109]
	v_mov_b32_e32 v229, v228
	v_cvt_pk_bf16_f32 v116, v148, v149
	v_cvt_pk_bf16_f32 v117, v144, v145
	v_cvt_pk_bf16_f32 v118, v150, v151
	v_cvt_pk_bf16_f32 v119, v146, v147
	v_lshl_add_u64 v[108:109], v[204:205], 1, v[108:109]
	v_mov_b32_e32 v110, v228
	v_mov_b32_e32 v111, v228
	global_store_dwordx4 v[108:109], v[116:119], off
	v_pk_mul_f32 v[102:103], v[102:103], v[110:111]
	v_pk_mul_f32 v[110:111], v[98:99], v[110:111]
	v_pk_mul_f32 v[116:117], v[100:101], v[228:229]
	s_and_b64 vcc, exec, s[42:43]
	v_pk_mul_f32 v[118:119], v[96:97], v[228:229]
	s_cbranch_vccnz .LBB0_177
	ds_swizzle_b32 v98, v116 offset:swizzle(SWAP,16)
	ds_swizzle_b32 v96, v118 offset:swizzle(SWAP,16)
	ds_swizzle_b32 v99, v117 offset:swizzle(SWAP,16)
	ds_swizzle_b32 v97, v119 offset:swizzle(SWAP,16)
	ds_swizzle_b32 v146, v102 offset:swizzle(SWAP,16)
	ds_swizzle_b32 v144, v110 offset:swizzle(SWAP,16)
	ds_swizzle_b32 v147, v103 offset:swizzle(SWAP,16)
	ds_swizzle_b32 v145, v111 offset:swizzle(SWAP,16)
	s_and_saveexec_b64 s[0:1], s[46:47]
	s_xor_b64 s[0:1], exec, s[0:1]
	s_cbranch_execz .LBB0_174
	s_and_saveexec_b64 s[4:5], s[44:45]
	s_cbranch_execz .LBB0_173
	s_waitcnt lgkmcnt(0)
	v_pk_mul_f32 v[98:99], v[124:125], v[98:99]
	v_pk_mul_f32 v[100:101], v[126:127], v[146:147]
	v_pk_fma_f32 v[116:117], v[116:117], v[120:121], v[98:99]
	v_pk_mul_f32 v[98:99], v[114:115], v[144:145]
	v_pk_mul_f32 v[96:97], v[112:113], v[96:97]
	v_pk_fma_f32 v[102:103], v[102:103], v[122:123], v[100:101]
	v_pk_fma_f32 v[110:111], v[110:111], v[106:107], v[98:99]
	v_pk_fma_f32 v[118:119], v[118:119], v[104:105], v[96:97]

.LBB0_174:
	s_andn2_saveexec_b64 s[0:1], s[0:1]
	s_cbranch_execz .LBB0_176
	s_waitcnt lgkmcnt(0)
	v_pk_mul_f32 v[98:99], v[124:125], v[98:99]
	v_pk_mul_f32 v[100:101], v[126:127], v[146:147]
	v_pk_fma_f32 v[116:117], v[116:117], v[120:121], v[98:99] neg_lo:[0,0,1] neg_hi:[0,0,1]
	v_pk_mul_f32 v[98:99], v[114:115], v[144:145]
	v_pk_mul_f32 v[96:97], v[112:113], v[96:97]
	v_pk_fma_f32 v[102:103], v[102:103], v[122:123], v[100:101] neg_lo:[0,0,1] neg_hi:[0,0,1]
	v_pk_fma_f32 v[110:111], v[110:111], v[106:107], v[98:99] neg_lo:[0,0,1] neg_hi:[0,0,1]
	v_pk_fma_f32 v[118:119], v[118:119], v[104:105], v[96:97] neg_lo:[0,0,1] neg_hi:[0,0,1]

.LBB0_177:
	s_and_b64 vcc, exec, s[40:41]
	s_cbranch_vccnz .LBB0_179
	s_waitcnt lgkmcnt(0)
	v_add_f32_e32 v96, v44, v116
	v_mul_f32_e32 v96, 0xbfb8aa3b, v96
	v_add_f32_e32 v97, v40, v118
	v_exp_f32_e32 v96, v96
	v_mul_f32_e32 v97, 0xbfb8aa3b, v97
	v_exp_f32_e32 v97, v97
	v_add_f32_e32 v98, v41, v119
	v_add_f32_e32 v96, 1.0, v96
	v_rcp_f32_e32 v116, v96
	v_add_f32_e32 v96, 1.0, v97
	v_add_f32_e32 v97, v45, v117
	v_mul_f32_e32 v97, 0xbfb8aa3b, v97
	v_exp_f32_e32 v97, v97
	v_mul_f32_e32 v98, 0xbfb8aa3b, v98
	v_exp_f32_e32 v98, v98
	v_rcp_f32_e32 v118, v96
	v_add_f32_e32 v96, 1.0, v97
	v_add_f32_e32 v97, v46, v102
	v_rcp_f32_e32 v117, v96
	v_add_f32_e32 v96, 1.0, v98
	v_mul_f32_e32 v97, 0xbfb8aa3b, v97
	v_add_f32_e32 v98, v42, v110
	v_exp_f32_e32 v97, v97
	v_mul_f32_e32 v98, 0xbfb8aa3b, v98
	v_exp_f32_e32 v98, v98
	v_rcp_f32_e32 v119, v96
	v_add_f32_e32 v96, 1.0, v97
	v_add_f32_e32 v97, v47, v103
	v_rcp_f32_e32 v102, v96
	v_add_f32_e32 v96, 1.0, v98
	v_mul_f32_e32 v97, 0xbfb8aa3b, v97
	v_add_f32_e32 v98, v43, v111
	v_exp_f32_e32 v97, v97
	v_mul_f32_e32 v98, 0xbfb8aa3b, v98
	v_exp_f32_e32 v98, v98
	v_rcp_f32_e32 v110, v96
	v_add_f32_e32 v96, 1.0, v97
	v_rcp_f32_e32 v103, v96
	v_add_f32_e32 v96, 1.0, v98
	v_rcp_f32_e32 v111, v96

.LBB0_189:
	s_and_b64 vcc, exec, s[40:41]
	s_cbranch_vccnz .LBB0_191
	s_waitcnt lgkmcnt(0)
	v_add_f32_e32 v136, v60, v228
	v_mul_f32_e32 v136, 0xbfb8aa3b, v136
	v_add_f32_e32 v137, v56, v230
	v_exp_f32_e32 v136, v136
	v_mul_f32_e32 v137, 0xbfb8aa3b, v137
	v_exp_f32_e32 v137, v137
	v_add_f32_e32 v138, v57, v231
	v_add_f32_e32 v136, 1.0, v136
	v_rcp_f32_e32 v228, v136
	v_add_f32_e32 v136, 1.0, v137
	v_add_f32_e32 v137, v61, v229
	v_mul_f32_e32 v137, 0xbfb8aa3b, v137
	v_exp_f32_e32 v137, v137
	v_mul_f32_e32 v138, 0xbfb8aa3b, v138
	v_exp_f32_e32 v138, v138
	v_rcp_f32_e32 v230, v136
	v_add_f32_e32 v136, 1.0, v137
	v_add_f32_e32 v137, v62, v142
	v_rcp_f32_e32 v229, v136
	v_add_f32_e32 v136, 1.0, v138
	v_mul_f32_e32 v137, 0xbfb8aa3b, v137
	v_add_f32_e32 v138, v58, v224
	v_exp_f32_e32 v137, v137
	v_mul_f32_e32 v138, 0xbfb8aa3b, v138
	v_exp_f32_e32 v138, v138
	v_rcp_f32_e32 v231, v136
	v_add_f32_e32 v136, 1.0, v137
	v_add_f32_e32 v137, v63, v143
	v_rcp_f32_e32 v142, v136
	v_add_f32_e32 v136, 1.0, v138
	v_mul_f32_e32 v137, 0xbfb8aa3b, v137
	v_add_f32_e32 v138, v59, v225
	v_exp_f32_e32 v137, v137
	v_mul_f32_e32 v138, 0xbfb8aa3b, v138
	v_exp_f32_e32 v138, v138
	v_rcp_f32_e32 v224, v136
	v_add_f32_e32 v136, 1.0, v137
	v_rcp_f32_e32 v143, v136
	v_add_f32_e32 v136, 1.0, v138
	v_rcp_f32_e32 v225, v136
.LBB0_191:
	s_waitcnt lgkmcnt(0)
	v_mov_b64_e32 v[136:137], s[52:53]
	v_mad_i64_i32 v[136:137], s[0:1], v220, s15, v[136:137]
	v_cvt_pk_bf16_f32 v138, v228, v229
	v_cvt_pk_bf16_f32 v139, v142, v143
	v_lshl_add_u64 v[136:137], v[204:205], 1, v[136:137]
	v_mov_b32_e32 v227, v226
	v_cvt_pk_bf16_f32 v140, v230, v231
	v_cvt_pk_bf16_f32 v141, v224, v225
	global_store_dwordx4 v[136:137], v[138:141], off
	s_and_b64 vcc, exec, s[42:43]
	v_pk_mul_f32 v[142:143], v[128:129], v[226:227]
	v_mov_b32_e32 v138, v226
	v_mov_b32_e32 v139, v226
	v_pk_mul_f32 v[134:135], v[134:135], v[138:139]
	v_pk_mul_f32 v[140:141], v[132:133], v[226:227]
	v_pk_mul_f32 v[138:139], v[130:131], v[138:139]
	s_cbranch_vccnz .LBB0_199
	ds_swizzle_b32 v130, v140 offset:swizzle(SWAP,16)
	ds_swizzle_b32 v128, v142 offset:swizzle(SWAP,16)
	ds_swizzle_b32 v131, v141 offset:swizzle(SWAP,16)
	ds_swizzle_b32 v129, v143 offset:swizzle(SWAP,16)
	ds_swizzle_b32 v224, v134 offset:swizzle(SWAP,16)
	ds_swizzle_b32 v220, v138 offset:swizzle(SWAP,16)
	ds_swizzle_b32 v225, v135 offset:swizzle(SWAP,16)
	ds_swizzle_b32 v221, v139 offset:swizzle(SWAP,16)
	s_and_saveexec_b64 s[0:1], s[46:47]
	s_xor_b64 s[0:1], exec, s[0:1]
	s_cbranch_execz .LBB0_196
	s_and_saveexec_b64 s[4:5], s[44:45]
	s_cbranch_execz .LBB0_195
	s_waitcnt lgkmcnt(0)
	v_pk_mul_f32 v[130:131], v[164:165], v[130:131]
	v_pk_mul_f32 v[132:133], v[166:167], v[224:225]
	v_pk_fma_f32 v[140:141], v[140:141], v[160:161], v[130:131]
	v_pk_mul_f32 v[130:131], v[150:151], v[220:221]
	v_pk_mul_f32 v[128:129], v[148:149], v[128:129]
	v_pk_fma_f32 v[134:135], v[134:135], v[162:163], v[132:133]
	v_pk_fma_f32 v[138:139], v[138:139], v[146:147], v[130:131]
	v_pk_fma_f32 v[142:143], v[142:143], v[144:145], v[128:129]

.LBB0_196:
	s_andn2_saveexec_b64 s[0:1], s[0:1]
	s_cbranch_execz .LBB0_198
	s_waitcnt lgkmcnt(0)
	v_pk_mul_f32 v[130:131], v[164:165], v[130:131]
	v_pk_mul_f32 v[132:133], v[166:167], v[224:225]
	v_pk_fma_f32 v[140:141], v[140:141], v[160:161], v[130:131] neg_lo:[0,0,1] neg_hi:[0,0,1]
	v_pk_mul_f32 v[130:131], v[150:151], v[220:221]
	v_pk_mul_f32 v[128:129], v[148:149], v[128:129]
	v_pk_fma_f32 v[134:135], v[134:135], v[162:163], v[132:133] neg_lo:[0,0,1] neg_hi:[0,0,1]
	v_pk_fma_f32 v[138:139], v[138:139], v[146:147], v[130:131] neg_lo:[0,0,1] neg_hi:[0,0,1]
	v_pk_fma_f32 v[142:143], v[142:143], v[144:145], v[128:129] neg_lo:[0,0,1] neg_hi:[0,0,1]

.LBB0_199:
	s_and_b64 vcc, exec, s[40:41]
	s_cbranch_vccnz .LBB0_201
	s_waitcnt lgkmcnt(0)
	v_add_f32_e32 v128, v44, v140
	v_mul_f32_e32 v128, 0xbfb8aa3b, v128
	v_add_f32_e32 v129, v40, v142
	v_exp_f32_e32 v128, v128
	v_mul_f32_e32 v129, 0xbfb8aa3b, v129
	v_exp_f32_e32 v129, v129
	v_add_f32_e32 v130, v41, v143
	v_add_f32_e32 v128, 1.0, v128
	v_rcp_f32_e32 v140, v128
	v_add_f32_e32 v128, 1.0, v129
	v_add_f32_e32 v129, v45, v141
	v_mul_f32_e32 v129, 0xbfb8aa3b, v129
	v_exp_f32_e32 v129, v129
	v_mul_f32_e32 v130, 0xbfb8aa3b, v130
	v_exp_f32_e32 v130, v130
	v_rcp_f32_e32 v142, v128
	v_add_f32_e32 v128, 1.0, v129
	v_add_f32_e32 v129, v46, v134
	v_rcp_f32_e32 v141, v128
	v_add_f32_e32 v128, 1.0, v130
	v_mul_f32_e32 v129, 0xbfb8aa3b, v129
	v_add_f32_e32 v130, v42, v138
	v_exp_f32_e32 v129, v129
	v_mul_f32_e32 v130, 0xbfb8aa3b, v130
	v_exp_f32_e32 v130, v130
	v_rcp_f32_e32 v143, v128
	v_add_f32_e32 v128, 1.0, v129
	v_add_f32_e32 v129, v47, v135
	v_rcp_f32_e32 v134, v128
	v_add_f32_e32 v128, 1.0, v130
	v_mul_f32_e32 v129, 0xbfb8aa3b, v129
	v_add_f32_e32 v130, v43, v139
	v_exp_f32_e32 v129, v129
	v_mul_f32_e32 v130, 0xbfb8aa3b, v130
	v_exp_f32_e32 v130, v130
	v_rcp_f32_e32 v138, v128
	v_add_f32_e32 v128, 1.0, v129
	v_rcp_f32_e32 v135, v128
	v_add_f32_e32 v128, 1.0, v130
	v_rcp_f32_e32 v139, v128
.LBB0_201:
	s_waitcnt lgkmcnt(0)
	v_cvt_pk_bf16_f32 v128, v140, v141
	v_cvt_pk_bf16_f32 v129, v134, v135
	v_cvt_pk_bf16_f32 v130, v142, v143
	v_cvt_pk_bf16_f32 v131, v138, v139
	global_store_dwordx4 v[136:137], v[128:131], off offset:256
	v_pk_mul_f32 v[94:95], v[94:95], v[222:223] op_sel_hi:[1,0]
	s_and_b64 vcc, exec, s[42:43]
	v_pk_mul_f32 v[130:131], v[92:93], v[222:223] op_sel_hi:[1,0]
	v_pk_mul_f32 v[128:129], v[90:91], v[222:223] op_sel_hi:[1,0]
	v_pk_mul_f32 v[132:133], v[88:89], v[222:223] op_sel_hi:[1,0]
	s_cbranch_vccnz .LBB0_209
	ds_swizzle_b32 v90, v130 offset:swizzle(SWAP,16)
	ds_swizzle_b32 v88, v132 offset:swizzle(SWAP,16)
	ds_swizzle_b32 v91, v131 offset:swizzle(SWAP,16)
	ds_swizzle_b32 v89, v133 offset:swizzle(SWAP,16)
	ds_swizzle_b32 v136, v94 offset:swizzle(SWAP,16)
	ds_swizzle_b32 v134, v128 offset:swizzle(SWAP,16)
	ds_swizzle_b32 v137, v95 offset:swizzle(SWAP,16)
	ds_swizzle_b32 v135, v129 offset:swizzle(SWAP,16)
	s_and_saveexec_b64 s[0:1], s[46:47]
	s_xor_b64 s[0:1], exec, s[0:1]
	s_cbranch_execz .LBB0_206
	s_and_saveexec_b64 s[4:5], s[44:45]
	s_cbranch_execz .LBB0_205
	s_waitcnt lgkmcnt(0)
	v_pk_mul_f32 v[90:91], v[116:117], v[90:91]
	v_pk_mul_f32 v[92:93], v[118:119], v[136:137]
	v_pk_fma_f32 v[130:131], v[130:131], v[108:109], v[90:91]
	v_pk_mul_f32 v[90:91], v[102:103], v[134:135]
	v_pk_mul_f32 v[88:89], v[100:101], v[88:89]
	v_pk_fma_f32 v[94:95], v[94:95], v[110:111], v[92:93]
	v_pk_fma_f32 v[128:129], v[128:129], v[98:99], v[90:91]
	v_pk_fma_f32 v[132:133], v[132:133], v[96:97], v[88:89]

.LBB0_206:
	s_andn2_saveexec_b64 s[0:1], s[0:1]
	s_cbranch_execz .LBB0_208
	s_waitcnt lgkmcnt(0)
	v_pk_mul_f32 v[90:91], v[116:117], v[90:91]
	v_pk_mul_f32 v[92:93], v[118:119], v[136:137]
	v_pk_fma_f32 v[130:131], v[130:131], v[108:109], v[90:91] neg_lo:[0,0,1] neg_hi:[0,0,1]
	v_pk_mul_f32 v[90:91], v[102:103], v[134:135]
	v_pk_mul_f32 v[88:89], v[100:101], v[88:89]
	v_pk_fma_f32 v[94:95], v[94:95], v[110:111], v[92:93] neg_lo:[0,0,1] neg_hi:[0,0,1]
	v_pk_fma_f32 v[128:129], v[128:129], v[98:99], v[90:91] neg_lo:[0,0,1] neg_hi:[0,0,1]
	v_pk_fma_f32 v[132:133], v[132:133], v[96:97], v[88:89] neg_lo:[0,0,1] neg_hi:[0,0,1]

.LBB0_209:
	s_and_b64 vcc, exec, s[40:41]
	s_cbranch_vccnz .LBB0_211
	s_waitcnt lgkmcnt(0)
	v_add_f32_e32 v88, v60, v130
	v_mul_f32_e32 v88, 0xbfb8aa3b, v88
	v_add_f32_e32 v89, v56, v132
	v_exp_f32_e32 v88, v88
	v_mul_f32_e32 v89, 0xbfb8aa3b, v89
	v_exp_f32_e32 v89, v89
	v_add_f32_e32 v90, v57, v133
	v_add_f32_e32 v88, 1.0, v88
	v_rcp_f32_e32 v130, v88
	v_add_f32_e32 v88, 1.0, v89
	v_add_f32_e32 v89, v61, v131
	v_mul_f32_e32 v89, 0xbfb8aa3b, v89
	v_exp_f32_e32 v89, v89
	v_mul_f32_e32 v90, 0xbfb8aa3b, v90
	v_exp_f32_e32 v90, v90
	v_rcp_f32_e32 v132, v88
	v_add_f32_e32 v88, 1.0, v89
	v_add_f32_e32 v89, v62, v94
	v_rcp_f32_e32 v131, v88
	v_add_f32_e32 v88, 1.0, v90
	v_mul_f32_e32 v89, 0xbfb8aa3b, v89
	v_add_f32_e32 v90, v58, v128
	v_exp_f32_e32 v89, v89
	v_mul_f32_e32 v90, 0xbfb8aa3b, v90
	v_exp_f32_e32 v90, v90
	v_rcp_f32_e32 v133, v88
	v_add_f32_e32 v88, 1.0, v89
	v_add_f32_e32 v89, v63, v95
	v_rcp_f32_e32 v94, v88
	v_add_f32_e32 v88, 1.0, v90
	v_mul_f32_e32 v89, 0xbfb8aa3b, v89
	v_add_f32_e32 v90, v59, v129
	v_exp_f32_e32 v89, v89
	v_mul_f32_e32 v90, 0xbfb8aa3b, v90
	v_exp_f32_e32 v90, v90
	v_rcp_f32_e32 v128, v88
	v_add_f32_e32 v88, 1.0, v89
	v_rcp_f32_e32 v95, v88
	v_add_f32_e32 v88, 1.0, v90
	v_rcp_f32_e32 v129, v88
.LBB0_211:
	s_waitcnt lgkmcnt(0)
	v_mov_b64_e32 v[88:89], s[52:53]
	v_mad_i64_i32 v[88:89], s[0:1], v216, s15, v[88:89]
	v_cvt_pk_bf16_f32 v90, v130, v131
	v_cvt_pk_bf16_f32 v91, v94, v95
	v_lshl_add_u64 v[88:89], v[204:205], 1, v[88:89]
	v_mov_b32_e32 v223, v222
	v_cvt_pk_bf16_f32 v92, v132, v133
	v_cvt_pk_bf16_f32 v93, v128, v129
	global_store_dwordx4 v[88:89], v[90:93], off
	s_and_b64 vcc, exec, s[42:43]
	v_pk_mul_f32 v[94:95], v[80:81], v[222:223]
	v_mov_b32_e32 v90, v222
	v_mov_b32_e32 v91, v222
	v_pk_mul_f32 v[86:87], v[86:87], v[90:91]
	v_pk_mul_f32 v[92:93], v[84:85], v[222:223]
	v_pk_mul_f32 v[90:91], v[82:83], v[90:91]
	s_cbranch_vccnz .LBB0_219
	ds_swizzle_b32 v82, v92 offset:swizzle(SWAP,16)
	ds_swizzle_b32 v80, v94 offset:swizzle(SWAP,16)
	ds_swizzle_b32 v83, v93 offset:swizzle(SWAP,16)
	ds_swizzle_b32 v81, v95 offset:swizzle(SWAP,16)
	ds_swizzle_b32 v130, v86 offset:swizzle(SWAP,16)
	ds_swizzle_b32 v128, v90 offset:swizzle(SWAP,16)
	ds_swizzle_b32 v131, v87 offset:swizzle(SWAP,16)
	ds_swizzle_b32 v129, v91 offset:swizzle(SWAP,16)
	s_and_saveexec_b64 s[0:1], s[46:47]
	s_xor_b64 s[0:1], exec, s[0:1]
	s_cbranch_execz .LBB0_216
	s_and_saveexec_b64 s[4:5], s[44:45]
	s_cbranch_execz .LBB0_215
	s_waitcnt lgkmcnt(0)
	v_pk_mul_f32 v[82:83], v[116:117], v[82:83]
	v_pk_mul_f32 v[84:85], v[118:119], v[130:131]
	v_pk_fma_f32 v[92:93], v[92:93], v[108:109], v[82:83]
	v_pk_mul_f32 v[82:83], v[102:103], v[128:129]
	v_pk_mul_f32 v[80:81], v[100:101], v[80:81]
	v_pk_fma_f32 v[86:87], v[86:87], v[110:111], v[84:85]
	v_pk_fma_f32 v[90:91], v[90:91], v[98:99], v[82:83]
	v_pk_fma_f32 v[94:95], v[94:95], v[96:97], v[80:81]

.LBB0_216:
	s_andn2_saveexec_b64 s[0:1], s[0:1]
	s_cbranch_execz .LBB0_218
	s_waitcnt lgkmcnt(0)
	v_pk_mul_f32 v[82:83], v[116:117], v[82:83]
	v_pk_mul_f32 v[84:85], v[118:119], v[130:131]
	v_pk_fma_f32 v[92:93], v[92:93], v[108:109], v[82:83] neg_lo:[0,0,1] neg_hi:[0,0,1]
	v_pk_mul_f32 v[82:83], v[102:103], v[128:129]
	v_pk_mul_f32 v[80:81], v[100:101], v[80:81]
	v_pk_fma_f32 v[86:87], v[86:87], v[110:111], v[84:85] neg_lo:[0,0,1] neg_hi:[0,0,1]
	v_pk_fma_f32 v[90:91], v[90:91], v[98:99], v[82:83] neg_lo:[0,0,1] neg_hi:[0,0,1]
	v_pk_fma_f32 v[94:95], v[94:95], v[96:97], v[80:81] neg_lo:[0,0,1] neg_hi:[0,0,1]

.LBB0_219:
	s_and_b64 vcc, exec, s[40:41]
	s_cbranch_vccnz .LBB0_221
	s_waitcnt lgkmcnt(0)
	v_add_f32_e32 v80, v44, v92
	v_mul_f32_e32 v80, 0xbfb8aa3b, v80
	v_add_f32_e32 v81, v40, v94
	v_exp_f32_e32 v80, v80
	v_mul_f32_e32 v81, 0xbfb8aa3b, v81
	v_exp_f32_e32 v81, v81
	v_add_f32_e32 v82, v41, v95
	v_add_f32_e32 v80, 1.0, v80
	v_rcp_f32_e32 v92, v80
	v_add_f32_e32 v80, 1.0, v81
	v_add_f32_e32 v81, v45, v93
	v_mul_f32_e32 v81, 0xbfb8aa3b, v81
	v_exp_f32_e32 v81, v81
	v_mul_f32_e32 v82, 0xbfb8aa3b, v82
	v_exp_f32_e32 v82, v82
	v_rcp_f32_e32 v94, v80
	v_add_f32_e32 v80, 1.0, v81
	v_add_f32_e32 v81, v46, v86
	v_rcp_f32_e32 v93, v80
	v_add_f32_e32 v80, 1.0, v82
	v_mul_f32_e32 v81, 0xbfb8aa3b, v81
	v_add_f32_e32 v82, v42, v90
	v_exp_f32_e32 v81, v81
	v_mul_f32_e32 v82, 0xbfb8aa3b, v82
	v_exp_f32_e32 v82, v82
	v_rcp_f32_e32 v95, v80
	v_add_f32_e32 v80, 1.0, v81
	v_add_f32_e32 v81, v47, v87
	v_rcp_f32_e32 v86, v80
	v_add_f32_e32 v80, 1.0, v82
	v_mul_f32_e32 v81, 0xbfb8aa3b, v81
	v_add_f32_e32 v82, v43, v91
	v_exp_f32_e32 v81, v81
	v_mul_f32_e32 v82, 0xbfb8aa3b, v82
	v_exp_f32_e32 v82, v82
	v_rcp_f32_e32 v90, v80
	v_add_f32_e32 v80, 1.0, v81
	v_rcp_f32_e32 v87, v80
	v_add_f32_e32 v80, 1.0, v82
	v_rcp_f32_e32 v91, v80

.LBB0_231:
	s_and_b64 vcc, exec, s[40:41]
	s_cbranch_vccnz .LBB0_233
	s_waitcnt lgkmcnt(0)
	v_add_f32_e32 v72, v60, v84
	v_mul_f32_e32 v72, 0xbfb8aa3b, v72
	v_add_f32_e32 v73, v56, v86
	v_exp_f32_e32 v72, v72
	v_mul_f32_e32 v73, 0xbfb8aa3b, v73
	v_exp_f32_e32 v73, v73
	v_add_f32_e32 v74, v57, v87
	v_add_f32_e32 v72, 1.0, v72
	v_rcp_f32_e32 v84, v72
	v_add_f32_e32 v72, 1.0, v73
	v_add_f32_e32 v73, v61, v85
	v_mul_f32_e32 v73, 0xbfb8aa3b, v73
	v_exp_f32_e32 v73, v73
	v_mul_f32_e32 v74, 0xbfb8aa3b, v74
	v_exp_f32_e32 v74, v74
	v_rcp_f32_e32 v86, v72
	v_add_f32_e32 v72, 1.0, v73
	v_add_f32_e32 v73, v62, v78
	v_rcp_f32_e32 v85, v72
	v_add_f32_e32 v72, 1.0, v74
	v_mul_f32_e32 v73, 0xbfb8aa3b, v73
	v_add_f32_e32 v74, v58, v82
	v_exp_f32_e32 v73, v73
	v_mul_f32_e32 v74, 0xbfb8aa3b, v74
	v_exp_f32_e32 v74, v74
	v_rcp_f32_e32 v87, v72
	v_add_f32_e32 v72, 1.0, v73
	v_add_f32_e32 v73, v63, v79
	v_rcp_f32_e32 v78, v72
	v_add_f32_e32 v72, 1.0, v74
	v_mul_f32_e32 v73, 0xbfb8aa3b, v73
	v_add_f32_e32 v74, v59, v83
	v_exp_f32_e32 v73, v73
	v_mul_f32_e32 v74, 0xbfb8aa3b, v74
	v_exp_f32_e32 v74, v74
	v_rcp_f32_e32 v82, v72
	v_add_f32_e32 v72, 1.0, v73
	v_rcp_f32_e32 v79, v72
	v_add_f32_e32 v72, 1.0, v74
	v_rcp_f32_e32 v83, v72
.LBB0_233:
	s_waitcnt lgkmcnt(0)
	v_mov_b64_e32 v[72:73], s[52:53]
	v_mad_i64_i32 v[72:73], s[0:1], v80, s15, v[72:73]
	v_cvt_pk_bf16_f32 v74, v84, v85
	v_cvt_pk_bf16_f32 v75, v78, v79
	v_lshl_add_u64 v[72:73], v[204:205], 1, v[72:73]
	v_mov_b32_e32 v219, v218
	v_cvt_pk_bf16_f32 v76, v86, v87
	v_cvt_pk_bf16_f32 v77, v82, v83
	global_store_dwordx4 v[72:73], v[74:77], off
	s_and_b64 vcc, exec, s[42:43]
	v_pk_mul_f32 v[78:79], v[64:65], v[218:219]
	v_mov_b32_e32 v74, v218
	v_mov_b32_e32 v75, v218
	v_pk_mul_f32 v[70:71], v[70:71], v[74:75]
	v_pk_mul_f32 v[76:77], v[68:69], v[218:219]
	v_pk_mul_f32 v[74:75], v[66:67], v[74:75]
	s_cbranch_vccnz .LBB0_241
	ds_swizzle_b32 v66, v76 offset:swizzle(SWAP,16)
	ds_swizzle_b32 v64, v78 offset:swizzle(SWAP,16)
	ds_swizzle_b32 v67, v77 offset:swizzle(SWAP,16)
	ds_swizzle_b32 v65, v79 offset:swizzle(SWAP,16)
	ds_swizzle_b32 v82, v70 offset:swizzle(SWAP,16)
	ds_swizzle_b32 v80, v74 offset:swizzle(SWAP,16)
	ds_swizzle_b32 v83, v71 offset:swizzle(SWAP,16)
	ds_swizzle_b32 v81, v75 offset:swizzle(SWAP,16)
	s_and_saveexec_b64 s[0:1], s[46:47]
	s_xor_b64 s[0:1], exec, s[0:1]
	s_cbranch_execz .LBB0_238
	s_and_saveexec_b64 s[4:5], s[44:45]
	s_cbranch_execz .LBB0_237
	s_waitcnt lgkmcnt(0)
	v_pk_mul_f32 v[66:67], v[172:173], v[66:67]
	v_pk_mul_f32 v[68:69], v[174:175], v[82:83]
	v_pk_fma_f32 v[76:77], v[76:77], v[168:169], v[66:67]
	v_pk_mul_f32 v[66:67], v[158:159], v[80:81]
	v_pk_mul_f32 v[64:65], v[156:157], v[64:65]
	v_pk_fma_f32 v[70:71], v[70:71], v[170:171], v[68:69]
	v_pk_fma_f32 v[74:75], v[74:75], v[154:155], v[66:67]
	v_pk_fma_f32 v[78:79], v[78:79], v[152:153], v[64:65]

.LBB0_238:
	s_andn2_saveexec_b64 s[0:1], s[0:1]
	s_cbranch_execz .LBB0_240
	s_waitcnt lgkmcnt(0)
	v_pk_mul_f32 v[66:67], v[172:173], v[66:67]
	v_pk_mul_f32 v[68:69], v[174:175], v[82:83]
	v_pk_fma_f32 v[76:77], v[76:77], v[168:169], v[66:67] neg_lo:[0,0,1] neg_hi:[0,0,1]
	v_pk_mul_f32 v[66:67], v[158:159], v[80:81]
	v_pk_mul_f32 v[64:65], v[156:157], v[64:65]
	v_pk_fma_f32 v[70:71], v[70:71], v[170:171], v[68:69] neg_lo:[0,0,1] neg_hi:[0,0,1]
	v_pk_fma_f32 v[74:75], v[74:75], v[154:155], v[66:67] neg_lo:[0,0,1] neg_hi:[0,0,1]
	v_pk_fma_f32 v[78:79], v[78:79], v[152:153], v[64:65] neg_lo:[0,0,1] neg_hi:[0,0,1]

.LBB0_241:
	s_and_b64 vcc, exec, s[40:41]
	s_cbranch_vccnz .LBB0_243
	s_waitcnt lgkmcnt(0)
	v_add_f32_e32 v64, v44, v76
	v_mul_f32_e32 v64, 0xbfb8aa3b, v64
	v_add_f32_e32 v65, v40, v78
	v_exp_f32_e32 v64, v64
	v_mul_f32_e32 v65, 0xbfb8aa3b, v65
	v_exp_f32_e32 v65, v65
	v_add_f32_e32 v66, v41, v79
	v_add_f32_e32 v64, 1.0, v64
	v_rcp_f32_e32 v76, v64
	v_add_f32_e32 v64, 1.0, v65
	v_add_f32_e32 v65, v45, v77
	v_mul_f32_e32 v65, 0xbfb8aa3b, v65
	v_exp_f32_e32 v65, v65
	v_mul_f32_e32 v66, 0xbfb8aa3b, v66
	v_exp_f32_e32 v66, v66
	v_rcp_f32_e32 v78, v64
	v_add_f32_e32 v64, 1.0, v65
	v_add_f32_e32 v65, v46, v70
	v_rcp_f32_e32 v77, v64
	v_add_f32_e32 v64, 1.0, v66
	v_mul_f32_e32 v65, 0xbfb8aa3b, v65
	v_add_f32_e32 v66, v42, v74
	v_exp_f32_e32 v65, v65
	v_mul_f32_e32 v66, 0xbfb8aa3b, v66
	v_exp_f32_e32 v66, v66
	v_rcp_f32_e32 v79, v64
	v_add_f32_e32 v64, 1.0, v65
	v_add_f32_e32 v65, v47, v71
	v_rcp_f32_e32 v70, v64
	v_add_f32_e32 v64, 1.0, v66
	v_mul_f32_e32 v65, 0xbfb8aa3b, v65
	v_add_f32_e32 v66, v43, v75
	v_exp_f32_e32 v65, v65
	v_mul_f32_e32 v66, 0xbfb8aa3b, v66
	v_exp_f32_e32 v66, v66
	v_rcp_f32_e32 v74, v64
	v_add_f32_e32 v64, 1.0, v65
	v_rcp_f32_e32 v71, v64
	v_add_f32_e32 v64, 1.0, v66
	v_rcp_f32_e32 v75, v64
.LBB0_243:
	s_waitcnt lgkmcnt(0)
	v_cvt_pk_bf16_f32 v64, v76, v77
	v_cvt_pk_bf16_f32 v65, v70, v71
	v_cvt_pk_bf16_f32 v66, v78, v79
	v_cvt_pk_bf16_f32 v67, v74, v75
	global_store_dwordx4 v[72:73], v[64:67], off offset:256
	v_pk_mul_f32 v[54:55], v[54:55], v[214:215] op_sel_hi:[1,0]
	s_and_b64 vcc, exec, s[42:43]
	v_pk_mul_f32 v[66:67], v[52:53], v[214:215] op_sel_hi:[1,0]
	v_pk_mul_f32 v[64:65], v[50:51], v[214:215] op_sel_hi:[1,0]
	v_pk_mul_f32 v[68:69], v[48:49], v[214:215] op_sel_hi:[1,0]
	s_cbranch_vccnz .LBB0_251
	ds_swizzle_b32 v50, v66 offset:swizzle(SWAP,16)
	ds_swizzle_b32 v48, v68 offset:swizzle(SWAP,16)
	ds_swizzle_b32 v51, v67 offset:swizzle(SWAP,16)
	ds_swizzle_b32 v49, v69 offset:swizzle(SWAP,16)
	ds_swizzle_b32 v72, v54 offset:swizzle(SWAP,16)
	ds_swizzle_b32 v70, v64 offset:swizzle(SWAP,16)
	ds_swizzle_b32 v73, v55 offset:swizzle(SWAP,16)
	ds_swizzle_b32 v71, v65 offset:swizzle(SWAP,16)
	s_and_saveexec_b64 s[0:1], s[46:47]
	s_xor_b64 s[0:1], exec, s[0:1]
	s_cbranch_execz .LBB0_248
	s_and_saveexec_b64 s[4:5], s[44:45]
	s_cbranch_execz .LBB0_247
	s_waitcnt lgkmcnt(0)
	v_pk_mul_f32 v[50:51], v[124:125], v[50:51]
	v_pk_mul_f32 v[52:53], v[126:127], v[72:73]
	v_pk_fma_f32 v[66:67], v[66:67], v[120:121], v[50:51]
	v_pk_mul_f32 v[50:51], v[114:115], v[70:71]
	v_pk_mul_f32 v[48:49], v[112:113], v[48:49]
	v_pk_fma_f32 v[54:55], v[54:55], v[122:123], v[52:53]
	v_pk_fma_f32 v[64:65], v[64:65], v[106:107], v[50:51]
	v_pk_fma_f32 v[68:69], v[68:69], v[104:105], v[48:49]

.LBB0_248:
	s_andn2_saveexec_b64 s[0:1], s[0:1]
	s_cbranch_execz .LBB0_250
	s_waitcnt lgkmcnt(0)
	v_pk_mul_f32 v[50:51], v[124:125], v[50:51]
	v_pk_mul_f32 v[52:53], v[126:127], v[72:73]
	v_pk_fma_f32 v[66:67], v[66:67], v[120:121], v[50:51] neg_lo:[0,0,1] neg_hi:[0,0,1]
	v_pk_mul_f32 v[50:51], v[114:115], v[70:71]
	v_pk_mul_f32 v[48:49], v[112:113], v[48:49]
	v_pk_fma_f32 v[54:55], v[54:55], v[122:123], v[52:53] neg_lo:[0,0,1] neg_hi:[0,0,1]
	v_pk_fma_f32 v[64:65], v[64:65], v[106:107], v[50:51] neg_lo:[0,0,1] neg_hi:[0,0,1]
	v_pk_fma_f32 v[68:69], v[68:69], v[104:105], v[48:49] neg_lo:[0,0,1] neg_hi:[0,0,1]

.LBB0_251:
	s_and_b64 vcc, exec, s[40:41]
	s_cbranch_vccnz .LBB0_253
	s_waitcnt lgkmcnt(0)
	v_add_f32_e32 v48, v60, v66
	v_mul_f32_e32 v48, 0xbfb8aa3b, v48
	v_add_f32_e32 v49, v56, v68
	v_exp_f32_e32 v48, v48
	v_mul_f32_e32 v49, 0xbfb8aa3b, v49
	v_exp_f32_e32 v49, v49
	v_add_f32_e32 v50, v57, v69
	v_add_f32_e32 v48, 1.0, v48
	v_rcp_f32_e32 v66, v48
	v_add_f32_e32 v48, 1.0, v49
	v_add_f32_e32 v49, v61, v67
	v_mul_f32_e32 v49, 0xbfb8aa3b, v49
	v_exp_f32_e32 v49, v49
	v_mul_f32_e32 v50, 0xbfb8aa3b, v50
	v_exp_f32_e32 v50, v50
	v_rcp_f32_e32 v68, v48
	v_add_f32_e32 v48, 1.0, v49
	v_add_f32_e32 v49, v62, v54
	v_rcp_f32_e32 v67, v48
	v_add_f32_e32 v48, 1.0, v50
	v_mul_f32_e32 v49, 0xbfb8aa3b, v49
	v_add_f32_e32 v50, v58, v64
	v_exp_f32_e32 v49, v49
	v_mul_f32_e32 v50, 0xbfb8aa3b, v50
	v_exp_f32_e32 v50, v50
	v_rcp_f32_e32 v69, v48
	v_add_f32_e32 v48, 1.0, v49
	v_add_f32_e32 v49, v63, v55
	v_rcp_f32_e32 v54, v48
	v_add_f32_e32 v48, 1.0, v50
	v_mul_f32_e32 v49, 0xbfb8aa3b, v49
	v_add_f32_e32 v50, v59, v65
	v_exp_f32_e32 v49, v49
	v_mul_f32_e32 v50, 0xbfb8aa3b, v50
	v_exp_f32_e32 v50, v50
	v_rcp_f32_e32 v64, v48
	v_add_f32_e32 v48, 1.0, v49
	v_rcp_f32_e32 v55, v48
	v_add_f32_e32 v48, 1.0, v50
	v_rcp_f32_e32 v65, v48
.LBB0_253:
	s_waitcnt lgkmcnt(0)
	v_mov_b64_e32 v[48:49], s[52:53]
	v_mad_i64_i32 v[48:49], s[0:1], v210, s15, v[48:49]
	v_cvt_pk_bf16_f32 v50, v66, v67
	v_cvt_pk_bf16_f32 v51, v54, v55
	v_lshl_add_u64 v[48:49], v[204:205], 1, v[48:49]
	v_mov_b32_e32 v215, v214
	v_cvt_pk_bf16_f32 v52, v68, v69
	v_cvt_pk_bf16_f32 v53, v64, v65
	global_store_dwordx4 v[48:49], v[50:53], off
	s_and_b64 vcc, exec, s[42:43]
	v_pk_mul_f32 v[54:55], v[32:33], v[214:215]
	v_mov_b32_e32 v50, v214
	v_mov_b32_e32 v51, v214
	v_pk_mul_f32 v[38:39], v[38:39], v[50:51]
	v_pk_mul_f32 v[52:53], v[36:37], v[214:215]
	v_pk_mul_f32 v[50:51], v[34:35], v[50:51]
	s_cbranch_vccnz .LBB0_261
	ds_swizzle_b32 v34, v52 offset:swizzle(SWAP,16)
	ds_swizzle_b32 v32, v54 offset:swizzle(SWAP,16)
	ds_swizzle_b32 v35, v53 offset:swizzle(SWAP,16)
	ds_swizzle_b32 v33, v55 offset:swizzle(SWAP,16)
	ds_swizzle_b32 v66, v38 offset:swizzle(SWAP,16)
	ds_swizzle_b32 v64, v50 offset:swizzle(SWAP,16)
	ds_swizzle_b32 v67, v39 offset:swizzle(SWAP,16)
	ds_swizzle_b32 v65, v51 offset:swizzle(SWAP,16)
	s_and_saveexec_b64 s[0:1], s[46:47]
	s_xor_b64 s[0:1], exec, s[0:1]
	s_cbranch_execz .LBB0_258
	s_and_saveexec_b64 s[4:5], s[44:45]
	s_cbranch_execz .LBB0_257
	s_waitcnt lgkmcnt(0)
	v_pk_mul_f32 v[34:35], v[124:125], v[34:35]
	v_pk_mul_f32 v[36:37], v[126:127], v[66:67]
	v_pk_fma_f32 v[52:53], v[52:53], v[120:121], v[34:35]
	v_pk_mul_f32 v[34:35], v[114:115], v[64:65]
	v_pk_mul_f32 v[32:33], v[112:113], v[32:33]
	v_pk_fma_f32 v[38:39], v[38:39], v[122:123], v[36:37]
	v_pk_fma_f32 v[50:51], v[50:51], v[106:107], v[34:35]
	v_pk_fma_f32 v[54:55], v[54:55], v[104:105], v[32:33]

.LBB0_258:
	s_andn2_saveexec_b64 s[0:1], s[0:1]
	s_cbranch_execz .LBB0_260
	s_waitcnt lgkmcnt(0)
	v_pk_mul_f32 v[34:35], v[124:125], v[34:35]
	v_pk_mul_f32 v[36:37], v[126:127], v[66:67]
	v_pk_fma_f32 v[52:53], v[52:53], v[120:121], v[34:35] neg_lo:[0,0,1] neg_hi:[0,0,1]
	v_pk_mul_f32 v[34:35], v[114:115], v[64:65]
	v_pk_mul_f32 v[32:33], v[112:113], v[32:33]
	v_pk_fma_f32 v[38:39], v[38:39], v[122:123], v[36:37] neg_lo:[0,0,1] neg_hi:[0,0,1]
	v_pk_fma_f32 v[50:51], v[50:51], v[106:107], v[34:35] neg_lo:[0,0,1] neg_hi:[0,0,1]
	v_pk_fma_f32 v[54:55], v[54:55], v[104:105], v[32:33] neg_lo:[0,0,1] neg_hi:[0,0,1]

.LBB0_261:
	s_and_b64 vcc, exec, s[40:41]
	s_cbranch_vccnz .LBB0_263
	s_waitcnt lgkmcnt(0)
	v_add_f32_e32 v32, v44, v52
	v_mul_f32_e32 v32, 0xbfb8aa3b, v32
	v_add_f32_e32 v33, v40, v54
	v_exp_f32_e32 v32, v32
	v_mul_f32_e32 v33, 0xbfb8aa3b, v33
	v_exp_f32_e32 v33, v33
	v_add_f32_e32 v34, v41, v55
	v_add_f32_e32 v32, 1.0, v32
	v_rcp_f32_e32 v52, v32
	v_add_f32_e32 v32, 1.0, v33
	v_add_f32_e32 v33, v45, v53
	v_mul_f32_e32 v33, 0xbfb8aa3b, v33
	v_exp_f32_e32 v33, v33
	v_mul_f32_e32 v34, 0xbfb8aa3b, v34
	v_exp_f32_e32 v34, v34
	v_rcp_f32_e32 v54, v32
	v_add_f32_e32 v32, 1.0, v33
	v_add_f32_e32 v33, v46, v38
	v_rcp_f32_e32 v53, v32
	v_add_f32_e32 v32, 1.0, v34
	v_mul_f32_e32 v33, 0xbfb8aa3b, v33
	v_add_f32_e32 v34, v42, v50
	v_exp_f32_e32 v33, v33
	v_mul_f32_e32 v34, 0xbfb8aa3b, v34
	v_exp_f32_e32 v34, v34
	v_rcp_f32_e32 v55, v32
	v_add_f32_e32 v32, 1.0, v33
	v_add_f32_e32 v33, v47, v39
	v_rcp_f32_e32 v38, v32
	v_add_f32_e32 v32, 1.0, v34
	v_mul_f32_e32 v33, 0xbfb8aa3b, v33
	v_add_f32_e32 v34, v43, v51
	v_exp_f32_e32 v33, v33
	v_mul_f32_e32 v34, 0xbfb8aa3b, v34
	v_exp_f32_e32 v34, v34
	v_rcp_f32_e32 v50, v32
	v_add_f32_e32 v32, 1.0, v33
	v_rcp_f32_e32 v39, v32
	v_add_f32_e32 v32, 1.0, v34
	v_rcp_f32_e32 v51, v32

.LBB0_273:
	s_and_b64 vcc, exec, s[40:41]
	s_cbranch_vccnz .LBB0_275
	s_waitcnt lgkmcnt(0)
	v_add_f32_e32 v24, v60, v34
	v_mul_f32_e32 v24, 0xbfb8aa3b, v24
	v_add_f32_e32 v25, v56, v36
	v_exp_f32_e32 v24, v24
	v_mul_f32_e32 v25, 0xbfb8aa3b, v25
	v_exp_f32_e32 v25, v25
	v_add_f32_e32 v26, v57, v37
	v_add_f32_e32 v24, 1.0, v24
	v_rcp_f32_e32 v34, v24
	v_add_f32_e32 v24, 1.0, v25
	v_add_f32_e32 v25, v61, v35
	v_mul_f32_e32 v25, 0xbfb8aa3b, v25
	v_exp_f32_e32 v25, v25
	v_mul_f32_e32 v26, 0xbfb8aa3b, v26
	v_exp_f32_e32 v26, v26
	v_rcp_f32_e32 v36, v24
	v_add_f32_e32 v24, 1.0, v25
	v_add_f32_e32 v25, v62, v30
	v_rcp_f32_e32 v35, v24
	v_add_f32_e32 v24, 1.0, v26
	v_mul_f32_e32 v25, 0xbfb8aa3b, v25
	v_add_f32_e32 v26, v58, v32
	v_exp_f32_e32 v25, v25
	v_mul_f32_e32 v26, 0xbfb8aa3b, v26
	v_exp_f32_e32 v26, v26
	v_rcp_f32_e32 v37, v24
	v_add_f32_e32 v24, 1.0, v25
	v_add_f32_e32 v25, v63, v31
	v_rcp_f32_e32 v30, v24
	v_add_f32_e32 v24, 1.0, v26
	v_mul_f32_e32 v25, 0xbfb8aa3b, v25
	v_add_f32_e32 v26, v59, v33
	v_exp_f32_e32 v25, v25
	v_mul_f32_e32 v26, 0xbfb8aa3b, v26
	v_exp_f32_e32 v26, v26
	v_rcp_f32_e32 v32, v24
	v_add_f32_e32 v24, 1.0, v25
	v_rcp_f32_e32 v31, v24
	v_add_f32_e32 v24, 1.0, v26
	v_rcp_f32_e32 v33, v24
.LBB0_275:
	s_waitcnt lgkmcnt(0)
	v_mov_b64_e32 v[24:25], s[52:53]
	v_mad_i64_i32 v[24:25], s[0:1], v202, s15, v[24:25]
	v_cvt_pk_bf16_f32 v26, v34, v35
	v_cvt_pk_bf16_f32 v27, v30, v31
	v_lshl_add_u64 v[24:25], v[204:205], 1, v[24:25]
	v_mov_b32_e32 v213, v212
	v_cvt_pk_bf16_f32 v28, v36, v37
	v_cvt_pk_bf16_f32 v29, v32, v33
	global_store_dwordx4 v[24:25], v[26:29], off
	s_and_b64 vcc, exec, s[42:43]
	v_pk_mul_f32 v[30:31], v[16:17], v[212:213]
	v_mov_b32_e32 v26, v212
	v_mov_b32_e32 v27, v212
	v_pk_mul_f32 v[22:23], v[22:23], v[26:27]
	v_pk_mul_f32 v[28:29], v[20:21], v[212:213]
	v_pk_mul_f32 v[26:27], v[18:19], v[26:27]
	s_cbranch_vccnz .LBB0_283
	ds_swizzle_b32 v18, v28 offset:swizzle(SWAP,16)
	ds_swizzle_b32 v16, v30 offset:swizzle(SWAP,16)
	ds_swizzle_b32 v19, v29 offset:swizzle(SWAP,16)
	ds_swizzle_b32 v17, v31 offset:swizzle(SWAP,16)
	ds_swizzle_b32 v34, v22 offset:swizzle(SWAP,16)
	ds_swizzle_b32 v32, v26 offset:swizzle(SWAP,16)
	ds_swizzle_b32 v35, v23 offset:swizzle(SWAP,16)
	ds_swizzle_b32 v33, v27 offset:swizzle(SWAP,16)
	s_and_saveexec_b64 s[0:1], s[46:47]
	s_xor_b64 s[0:1], exec, s[0:1]
	s_cbranch_execz .LBB0_280
	s_and_saveexec_b64 s[4:5], s[44:45]
	s_cbranch_execz .LBB0_279
	s_waitcnt lgkmcnt(0)
	v_pk_mul_f32 v[18:19], v[164:165], v[18:19]
	v_pk_mul_f32 v[20:21], v[166:167], v[34:35]
	v_pk_fma_f32 v[28:29], v[28:29], v[160:161], v[18:19]
	v_pk_mul_f32 v[18:19], v[150:151], v[32:33]
	v_pk_mul_f32 v[16:17], v[148:149], v[16:17]
	v_pk_fma_f32 v[22:23], v[22:23], v[162:163], v[20:21]
	v_pk_fma_f32 v[26:27], v[26:27], v[146:147], v[18:19]
	v_pk_fma_f32 v[30:31], v[30:31], v[144:145], v[16:17]

.LBB0_280:
	s_andn2_saveexec_b64 s[0:1], s[0:1]
	s_cbranch_execz .LBB0_282
	s_waitcnt lgkmcnt(0)
	v_pk_mul_f32 v[18:19], v[164:165], v[18:19]
	v_pk_mul_f32 v[20:21], v[166:167], v[34:35]
	v_pk_fma_f32 v[28:29], v[28:29], v[160:161], v[18:19] neg_lo:[0,0,1] neg_hi:[0,0,1]
	v_pk_mul_f32 v[18:19], v[150:151], v[32:33]
	v_pk_mul_f32 v[16:17], v[148:149], v[16:17]
	v_pk_fma_f32 v[22:23], v[22:23], v[162:163], v[20:21] neg_lo:[0,0,1] neg_hi:[0,0,1]
	v_pk_fma_f32 v[26:27], v[26:27], v[146:147], v[18:19] neg_lo:[0,0,1] neg_hi:[0,0,1]
	v_pk_fma_f32 v[30:31], v[30:31], v[144:145], v[16:17] neg_lo:[0,0,1] neg_hi:[0,0,1]

.LBB0_283:
	s_and_b64 vcc, exec, s[40:41]
	s_cbranch_vccnz .LBB0_285
	s_waitcnt lgkmcnt(0)
	v_add_f32_e32 v16, v44, v28
	v_mul_f32_e32 v16, 0xbfb8aa3b, v16
	v_add_f32_e32 v17, v40, v30
	v_exp_f32_e32 v16, v16
	v_mul_f32_e32 v17, 0xbfb8aa3b, v17
	v_exp_f32_e32 v17, v17
	v_add_f32_e32 v18, v41, v31
	v_add_f32_e32 v16, 1.0, v16
	v_rcp_f32_e32 v28, v16
	v_add_f32_e32 v16, 1.0, v17
	v_add_f32_e32 v17, v45, v29
	v_mul_f32_e32 v17, 0xbfb8aa3b, v17
	v_exp_f32_e32 v17, v17
	v_mul_f32_e32 v18, 0xbfb8aa3b, v18
	v_exp_f32_e32 v18, v18
	v_rcp_f32_e32 v30, v16
	v_add_f32_e32 v16, 1.0, v17
	v_add_f32_e32 v17, v46, v22
	v_rcp_f32_e32 v29, v16
	v_add_f32_e32 v16, 1.0, v18
	v_mul_f32_e32 v17, 0xbfb8aa3b, v17
	v_add_f32_e32 v18, v42, v26
	v_exp_f32_e32 v17, v17
	v_mul_f32_e32 v18, 0xbfb8aa3b, v18
	v_exp_f32_e32 v18, v18
	v_rcp_f32_e32 v31, v16
	v_add_f32_e32 v16, 1.0, v17
	v_add_f32_e32 v17, v47, v23
	v_rcp_f32_e32 v22, v16
	v_add_f32_e32 v16, 1.0, v18
	v_mul_f32_e32 v17, 0xbfb8aa3b, v17
	v_add_f32_e32 v18, v43, v27
	v_exp_f32_e32 v17, v17
	v_mul_f32_e32 v18, 0xbfb8aa3b, v18
	v_exp_f32_e32 v18, v18
	v_rcp_f32_e32 v26, v16
	v_add_f32_e32 v16, 1.0, v17
	v_rcp_f32_e32 v23, v16
	v_add_f32_e32 v16, 1.0, v18
	v_rcp_f32_e32 v27, v16
.LBB0_285:
	s_waitcnt lgkmcnt(0)
	v_cvt_pk_bf16_f32 v16, v28, v29
	v_cvt_pk_bf16_f32 v17, v22, v23
	v_cvt_pk_bf16_f32 v18, v30, v31
	v_cvt_pk_bf16_f32 v19, v26, v27
	global_store_dwordx4 v[24:25], v[16:19], off offset:256
	v_pk_mul_f32 v[14:15], v[14:15], v[208:209] op_sel_hi:[1,0]
	s_and_b64 vcc, exec, s[42:43]
	v_pk_mul_f32 v[18:19], v[12:13], v[208:209] op_sel_hi:[1,0]
	v_pk_mul_f32 v[16:17], v[10:11], v[208:209] op_sel_hi:[1,0]
	v_pk_mul_f32 v[20:21], v[8:9], v[208:209] op_sel_hi:[1,0]
	s_cbranch_vccnz .LBB0_293
	ds_swizzle_b32 v10, v18 offset:swizzle(SWAP,16)
	ds_swizzle_b32 v8, v20 offset:swizzle(SWAP,16)
	ds_swizzle_b32 v11, v19 offset:swizzle(SWAP,16)
	ds_swizzle_b32 v9, v21 offset:swizzle(SWAP,16)
	ds_swizzle_b32 v24, v14 offset:swizzle(SWAP,16)
	ds_swizzle_b32 v22, v16 offset:swizzle(SWAP,16)
	ds_swizzle_b32 v25, v15 offset:swizzle(SWAP,16)
	ds_swizzle_b32 v23, v17 offset:swizzle(SWAP,16)
	s_and_saveexec_b64 s[0:1], s[46:47]
	s_xor_b64 s[0:1], exec, s[0:1]
	s_cbranch_execz .LBB0_290
	s_and_saveexec_b64 s[4:5], s[44:45]
	s_cbranch_execz .LBB0_289
	s_waitcnt lgkmcnt(0)
	v_pk_mul_f32 v[10:11], v[116:117], v[10:11]
	v_pk_mul_f32 v[12:13], v[118:119], v[24:25]
	v_pk_fma_f32 v[18:19], v[18:19], v[108:109], v[10:11]
	v_pk_mul_f32 v[10:11], v[102:103], v[22:23]
	v_pk_mul_f32 v[8:9], v[100:101], v[8:9]
	v_pk_fma_f32 v[14:15], v[14:15], v[110:111], v[12:13]
	v_pk_fma_f32 v[16:17], v[16:17], v[98:99], v[10:11]
	v_pk_fma_f32 v[20:21], v[20:21], v[96:97], v[8:9]

.LBB0_290:
	s_andn2_saveexec_b64 s[0:1], s[0:1]
	s_cbranch_execz .LBB0_292
	s_waitcnt lgkmcnt(0)
	v_pk_mul_f32 v[10:11], v[116:117], v[10:11]
	v_pk_mul_f32 v[12:13], v[118:119], v[24:25]
	v_pk_fma_f32 v[18:19], v[18:19], v[108:109], v[10:11] neg_lo:[0,0,1] neg_hi:[0,0,1]
	v_pk_mul_f32 v[10:11], v[102:103], v[22:23]
	v_pk_mul_f32 v[8:9], v[100:101], v[8:9]
	v_pk_fma_f32 v[14:15], v[14:15], v[110:111], v[12:13] neg_lo:[0,0,1] neg_hi:[0,0,1]
	v_pk_fma_f32 v[16:17], v[16:17], v[98:99], v[10:11] neg_lo:[0,0,1] neg_hi:[0,0,1]
	v_pk_fma_f32 v[20:21], v[20:21], v[96:97], v[8:9] neg_lo:[0,0,1] neg_hi:[0,0,1]

.LBB0_293:
	s_and_b64 vcc, exec, s[40:41]
	s_cbranch_vccnz .LBB0_295
	s_waitcnt lgkmcnt(0)
	v_add_f32_e32 v8, v60, v18
	v_mul_f32_e32 v8, 0xbfb8aa3b, v8
	v_add_f32_e32 v9, v56, v20
	v_exp_f32_e32 v8, v8
	v_mul_f32_e32 v9, 0xbfb8aa3b, v9
	v_exp_f32_e32 v9, v9
	v_add_f32_e32 v10, v57, v21
	v_add_f32_e32 v8, 1.0, v8
	v_rcp_f32_e32 v18, v8
	v_add_f32_e32 v8, 1.0, v9
	v_add_f32_e32 v9, v61, v19
	v_mul_f32_e32 v9, 0xbfb8aa3b, v9
	v_exp_f32_e32 v9, v9
	v_mul_f32_e32 v10, 0xbfb8aa3b, v10
	v_exp_f32_e32 v10, v10
	v_rcp_f32_e32 v20, v8
	v_add_f32_e32 v8, 1.0, v9
	v_add_f32_e32 v9, v62, v14
	v_rcp_f32_e32 v19, v8
	v_add_f32_e32 v8, 1.0, v10
	v_mul_f32_e32 v9, 0xbfb8aa3b, v9
	v_add_f32_e32 v10, v58, v16
	v_exp_f32_e32 v9, v9
	v_mul_f32_e32 v10, 0xbfb8aa3b, v10
	v_exp_f32_e32 v10, v10
	v_rcp_f32_e32 v21, v8
	v_add_f32_e32 v8, 1.0, v9
	v_add_f32_e32 v9, v63, v15
	v_rcp_f32_e32 v14, v8
	v_add_f32_e32 v8, 1.0, v10
	v_mul_f32_e32 v9, 0xbfb8aa3b, v9
	v_add_f32_e32 v10, v59, v17
	v_exp_f32_e32 v9, v9
	v_mul_f32_e32 v10, 0xbfb8aa3b, v10
	v_exp_f32_e32 v10, v10
	v_rcp_f32_e32 v16, v8
	v_add_f32_e32 v8, 1.0, v9
	v_rcp_f32_e32 v15, v8
	v_add_f32_e32 v8, 1.0, v10
	v_rcp_f32_e32 v17, v8
.LBB0_295:
	s_waitcnt lgkmcnt(0)
	v_mov_b64_e32 v[8:9], s[52:53]
	v_mad_i64_i32 v[8:9], s[0:1], v200, s15, v[8:9]
	v_cvt_pk_bf16_f32 v10, v18, v19
	v_cvt_pk_bf16_f32 v11, v14, v15
	v_lshl_add_u64 v[8:9], v[204:205], 1, v[8:9]
	v_mov_b32_e32 v209, v208
	v_cvt_pk_bf16_f32 v12, v20, v21
	v_cvt_pk_bf16_f32 v13, v16, v17
	global_store_dwordx4 v[8:9], v[10:13], off
	s_and_b64 vcc, exec, s[42:43]
	v_pk_mul_f32 v[14:15], v[0:1], v[208:209]
	v_mov_b32_e32 v10, v208
	v_mov_b32_e32 v11, v208
	v_pk_mul_f32 v[6:7], v[6:7], v[10:11]
	v_pk_mul_f32 v[12:13], v[4:5], v[208:209]
	v_pk_mul_f32 v[10:11], v[2:3], v[10:11]
	s_cbranch_vccnz .LBB0_303
	ds_swizzle_b32 v2, v12 offset:swizzle(SWAP,16)
	ds_swizzle_b32 v0, v14 offset:swizzle(SWAP,16)
	ds_swizzle_b32 v3, v13 offset:swizzle(SWAP,16)
	ds_swizzle_b32 v1, v15 offset:swizzle(SWAP,16)
	ds_swizzle_b32 v18, v6 offset:swizzle(SWAP,16)
	ds_swizzle_b32 v16, v10 offset:swizzle(SWAP,16)
	ds_swizzle_b32 v19, v7 offset:swizzle(SWAP,16)
	ds_swizzle_b32 v17, v11 offset:swizzle(SWAP,16)
	s_and_saveexec_b64 s[0:1], s[46:47]
	s_xor_b64 s[0:1], exec, s[0:1]
	s_cbranch_execz .LBB0_300
	s_and_saveexec_b64 s[4:5], s[44:45]
	s_cbranch_execz .LBB0_299
	s_waitcnt lgkmcnt(0)
	v_pk_mul_f32 v[2:3], v[116:117], v[2:3]
	v_pk_mul_f32 v[4:5], v[118:119], v[18:19]
	v_pk_fma_f32 v[12:13], v[12:13], v[108:109], v[2:3]
	v_pk_mul_f32 v[2:3], v[102:103], v[16:17]
	v_pk_mul_f32 v[0:1], v[100:101], v[0:1]
	v_pk_fma_f32 v[6:7], v[6:7], v[110:111], v[4:5]
	v_pk_fma_f32 v[10:11], v[10:11], v[98:99], v[2:3]
	v_pk_fma_f32 v[14:15], v[14:15], v[96:97], v[0:1]

.LBB0_300:
	s_andn2_saveexec_b64 s[0:1], s[0:1]
	s_cbranch_execz .LBB0_302
	s_waitcnt lgkmcnt(0)
	v_pk_mul_f32 v[2:3], v[116:117], v[2:3]
	v_pk_mul_f32 v[4:5], v[118:119], v[18:19]
	v_pk_fma_f32 v[12:13], v[12:13], v[108:109], v[2:3] neg_lo:[0,0,1] neg_hi:[0,0,1]
	v_pk_mul_f32 v[2:3], v[102:103], v[16:17]
	v_pk_mul_f32 v[0:1], v[100:101], v[0:1]
	v_pk_fma_f32 v[6:7], v[6:7], v[110:111], v[4:5] neg_lo:[0,0,1] neg_hi:[0,0,1]
	v_pk_fma_f32 v[10:11], v[10:11], v[98:99], v[2:3] neg_lo:[0,0,1] neg_hi:[0,0,1]
	v_pk_fma_f32 v[14:15], v[14:15], v[96:97], v[0:1] neg_lo:[0,0,1] neg_hi:[0,0,1]

.LBB0_303:
	s_and_b64 vcc, exec, s[40:41]
	s_cbranch_vccnz .LBB0_305
	s_waitcnt lgkmcnt(0)
	v_add_f32_e32 v0, v44, v12
	v_mul_f32_e32 v0, 0xbfb8aa3b, v0
	v_add_f32_e32 v1, v40, v14
	v_exp_f32_e32 v0, v0
	v_mul_f32_e32 v1, 0xbfb8aa3b, v1
	v_exp_f32_e32 v1, v1
	v_add_f32_e32 v2, v41, v15
	v_add_f32_e32 v0, 1.0, v0
	v_rcp_f32_e32 v12, v0
	v_add_f32_e32 v0, 1.0, v1
	v_add_f32_e32 v1, v45, v13
	v_mul_f32_e32 v1, 0xbfb8aa3b, v1
	v_exp_f32_e32 v1, v1
	v_mul_f32_e32 v2, 0xbfb8aa3b, v2
	v_exp_f32_e32 v2, v2
	v_rcp_f32_e32 v14, v0
	v_add_f32_e32 v0, 1.0, v1
	v_add_f32_e32 v1, v46, v6
	v_rcp_f32_e32 v13, v0
	v_add_f32_e32 v0, 1.0, v2
	v_mul_f32_e32 v1, 0xbfb8aa3b, v1
	v_add_f32_e32 v2, v42, v10
	v_exp_f32_e32 v1, v1
	v_mul_f32_e32 v2, 0xbfb8aa3b, v2
	v_exp_f32_e32 v2, v2
	v_rcp_f32_e32 v15, v0
	v_add_f32_e32 v0, 1.0, v1
	v_add_f32_e32 v1, v47, v7
	v_rcp_f32_e32 v6, v0
	v_add_f32_e32 v0, 1.0, v2
	v_mul_f32_e32 v1, 0xbfb8aa3b, v1
	v_add_f32_e32 v2, v43, v11
	v_exp_f32_e32 v1, v1
	v_mul_f32_e32 v2, 0xbfb8aa3b, v2
	v_exp_f32_e32 v2, v2
	v_rcp_f32_e32 v10, v0
	v_add_f32_e32 v0, 1.0, v1
	v_rcp_f32_e32 v7, v0
	v_add_f32_e32 v0, 1.0, v2
	v_rcp_f32_e32 v11, v0
